# UP epilogue: rstd^2 folded into the reciprocal (rcp((1+e)*(mean+eps))), one packed multiply per pair less; MRG epilogues: canonicalising v_max before max(gate,1e-30) removed
# speedup vs baseline: 1.0125x; 1.0125x over previous
.LBB0_45:
	s_cmpk_lg_i32 s44, 0x400
	s_cbranch_scc1 .LBB0_44
	v_mov_b32_e32 v220, v214
	v_mov_b32_e32 v236, v215
	s_nop 0
	v_lshlrev_b32_e32 v0, 10, v236
	v_ashrrev_i32_e32 v221, 31, v220
	v_and_b32_e32 v0, 0x1ffc00, v0
	v_ashrrev_i32_e32 v136, 11, v236
	v_lshl_add_u64 v[134:135], v[0:1], 0, v[220:221]
	v_mad_i64_i32 v[134:135], s[46:47], v136, s61, v[134:135]
	v_lshlrev_b64 v[134:135], 1, v[134:135]
	v_lshl_add_u64 v[136:137], s[4:5], 0, v[134:135]
	v_add_u32_e32 v0, 16, v236
	v_lshl_add_u64 v[134:135], s[10:11], 0, v[134:135]
	global_load_dwordx4 v[174:177], v[136:137], off
	global_load_dwordx4 v[178:181], v[136:137], off offset:256
	global_load_dwordx4 v[182:185], v[134:135], off
	global_load_dwordx4 v[186:189], v[134:135], off offset:256
	v_ashrrev_i32_e32 v136, 11, v0
	v_lshlrev_b32_e32 v0, 10, v0
	v_and_b32_e32 v0, 0x1ffc00, v0
	v_lshl_add_u64 v[134:135], v[0:1], 0, v[220:221]
	v_mad_i64_i32 v[134:135], s[46:47], v136, s61, v[134:135]
	v_lshlrev_b64 v[134:135], 1, v[134:135]
	v_lshl_add_u64 v[136:137], s[4:5], 0, v[134:135]
	v_add_u32_e32 v0, 32, v236
	v_lshl_add_u64 v[134:135], s[10:11], 0, v[134:135]
	global_load_dwordx4 v[190:193], v[136:137], off
	global_load_dwordx4 v[166:169], v[136:137], off offset:256
	global_load_dwordx4 v[194:197], v[134:135], off
	global_load_dwordx4 v[170:173], v[134:135], off offset:256
	v_ashrrev_i32_e32 v136, 11, v0
	v_lshlrev_b32_e32 v0, 10, v0
	v_and_b32_e32 v0, 0x1ffc00, v0
	v_lshl_add_u64 v[134:135], v[0:1], 0, v[220:221]
	v_mad_i64_i32 v[134:135], s[46:47], v136, s61, v[134:135]
	v_lshlrev_b64 v[134:135], 1, v[134:135]
	v_lshl_add_u64 v[136:137], s[4:5], 0, v[134:135]
	v_add_u32_e32 v0, 48, v236
	v_lshl_add_u64 v[134:135], s[10:11], 0, v[134:135]
	global_load_dwordx4 v[158:161], v[136:137], off
	global_load_dwordx4 v[150:153], v[136:137], off offset:256
	global_load_dwordx4 v[162:165], v[134:135], off
	global_load_dwordx4 v[154:157], v[134:135], off offset:256
	v_ashrrev_i32_e32 v136, 11, v0
	v_lshlrev_b32_e32 v0, 10, v0
	v_and_b32_e32 v0, 0x1ffc00, v0
	v_lshl_add_u64 v[134:135], v[0:1], 0, v[220:221]
	v_mad_i64_i32 v[134:135], s[46:47], v136, s61, v[134:135]
	v_lshlrev_b64 v[134:135], 1, v[134:135]
	v_lshl_add_u64 v[136:137], s[4:5], 0, v[134:135]
	v_lshl_add_u64 v[138:139], s[10:11], 0, v[134:135]
	global_load_dwordx4 v[142:145], v[136:137], off
	s_nop 0
	global_load_dwordx4 v[134:137], v[136:137], off offset:256
	s_nop 0
	global_load_dwordx4 v[146:149], v[138:139], off
	s_nop 0
	global_load_dwordx4 v[138:141], v[138:139], off offset:256
	s_waitcnt vmcnt(0)
	v_lshlrev_b32_e32 v0, 16, v182
	v_max_f32_e32 v0, 0xda24260, v0
	v_rcp_f32_e32 v202, v0
	v_and_b32_e32 v0, 0xffff0000, v182
	v_max_f32_e32 v0, 0xda24260, v0
	v_rcp_f32_e32 v203, v0
	v_lshlrev_b32_e32 v0, 16, v183
	v_max_f32_e32 v0, 0xda24260, v0
	v_rcp_f32_e32 v182, v0
	v_and_b32_e32 v0, 0xffff0000, v183
	v_max_f32_e32 v0, 0xda24260, v0
	v_rcp_f32_e32 v183, v0
	v_lshlrev_b32_e32 v0, 16, v184
	v_max_f32_e32 v0, 0xda24260, v0
	v_rcp_f32_e32 v238, v0
	v_and_b32_e32 v0, 0xffff0000, v184
	v_max_f32_e32 v0, 0xda24260, v0
	v_rcp_f32_e32 v239, v0
	v_lshlrev_b32_e32 v0, 16, v185
	v_max_f32_e32 v0, 0xda24260, v0
	v_rcp_f32_e32 v184, v0
	v_and_b32_e32 v0, 0xffff0000, v185
	v_max_f32_e32 v0, 0xda24260, v0
	v_lshlrev_b32_e32 v240, 16, v174
	v_and_b32_e32 v241, 0xffff0000, v174
	v_lshlrev_b32_e32 v174, 16, v175
	v_and_b32_e32 v175, 0xffff0000, v175
	v_rcp_f32_e32 v185, v0
	v_pk_mul_f32 v[174:175], v[182:183], v[174:175]
	v_lshlrev_b32_e32 v0, 16, v186
	v_pk_mul_f32 v[132:133], v[132:133], v[174:175]
	v_lshlrev_b32_e32 v174, 16, v176
	v_and_b32_e32 v175, 0xffff0000, v176
	v_pk_mul_f32 v[174:175], v[238:239], v[174:175]
	v_pk_mul_f32 v[126:127], v[126:127], v[174:175]
	v_lshlrev_b32_e32 v174, 16, v177
	v_and_b32_e32 v175, 0xffff0000, v177
	v_pk_mul_f32 v[174:175], v[184:185], v[174:175]
	v_max_f32_e32 v0, 0xda24260, v0
	v_pk_mul_f32 v[128:129], v[128:129], v[174:175]
	v_rcp_f32_e32 v174, v0
	v_and_b32_e32 v0, 0xffff0000, v186
	v_max_f32_e32 v0, 0xda24260, v0
	v_rcp_f32_e32 v175, v0
	v_lshlrev_b32_e32 v0, 16, v187
	v_max_f32_e32 v0, 0xda24260, v0
	v_rcp_f32_e32 v176, v0
	v_and_b32_e32 v0, 0xffff0000, v187
	v_max_f32_e32 v0, 0xda24260, v0
	v_rcp_f32_e32 v177, v0
	v_lshlrev_b32_e32 v0, 16, v188
	v_max_f32_e32 v0, 0xda24260, v0
	v_rcp_f32_e32 v182, v0
	v_and_b32_e32 v0, 0xffff0000, v188
	v_max_f32_e32 v0, 0xda24260, v0
	v_rcp_f32_e32 v183, v0
	v_lshlrev_b32_e32 v0, 16, v189
	v_max_f32_e32 v0, 0xda24260, v0
	v_rcp_f32_e32 v184, v0
	v_and_b32_e32 v0, 0xffff0000, v189
	v_lshlrev_b32_e32 v186, 16, v178
	v_and_b32_e32 v187, 0xffff0000, v178
	v_pk_mul_f32 v[174:175], v[174:175], v[186:187]
	v_max_f32_e32 v0, 0xda24260, v0
	v_pk_mul_f32 v[122:123], v[122:123], v[174:175]
	v_lshlrev_b32_e32 v174, 16, v179
	v_and_b32_e32 v175, 0xffff0000, v179
	v_rcp_f32_e32 v185, v0
	v_pk_mul_f32 v[174:175], v[176:177], v[174:175]
	v_lshlrev_b32_e32 v0, 16, v194
	v_pk_mul_f32 v[124:125], v[124:125], v[174:175]
	v_lshlrev_b32_e32 v174, 16, v180
	v_and_b32_e32 v175, 0xffff0000, v180
	v_pk_mul_f32 v[174:175], v[182:183], v[174:175]
	v_pk_mul_f32 v[118:119], v[118:119], v[174:175]
	v_lshlrev_b32_e32 v174, 16, v181
	v_and_b32_e32 v175, 0xffff0000, v181
	v_pk_mul_f32 v[174:175], v[184:185], v[174:175]
	v_max_f32_e32 v0, 0xda24260, v0
	v_pk_mul_f32 v[120:121], v[120:121], v[174:175]
	v_rcp_f32_e32 v174, v0
	v_and_b32_e32 v0, 0xffff0000, v194
	v_max_f32_e32 v0, 0xda24260, v0
	v_rcp_f32_e32 v175, v0
	v_lshlrev_b32_e32 v0, 16, v195
	v_max_f32_e32 v0, 0xda24260, v0
	v_rcp_f32_e32 v176, v0
	v_and_b32_e32 v0, 0xffff0000, v195
	v_max_f32_e32 v0, 0xda24260, v0
	v_rcp_f32_e32 v177, v0
	v_lshlrev_b32_e32 v0, 16, v196
	v_max_f32_e32 v0, 0xda24260, v0
	v_rcp_f32_e32 v178, v0
	v_and_b32_e32 v0, 0xffff0000, v196
	v_max_f32_e32 v0, 0xda24260, v0
	v_rcp_f32_e32 v179, v0
	v_lshlrev_b32_e32 v0, 16, v197
	v_max_f32_e32 v0, 0xda24260, v0
	v_rcp_f32_e32 v180, v0
	v_and_b32_e32 v0, 0xffff0000, v197
	v_lshlrev_b32_e32 v182, 16, v190
	v_and_b32_e32 v183, 0xffff0000, v190
	v_pk_mul_f32 v[174:175], v[174:175], v[182:183]
	v_max_f32_e32 v0, 0xda24260, v0
	v_pk_mul_f32 v[114:115], v[114:115], v[174:175]
	v_lshlrev_b32_e32 v174, 16, v191
	v_and_b32_e32 v175, 0xffff0000, v191
	v_rcp_f32_e32 v181, v0
	v_pk_mul_f32 v[174:175], v[176:177], v[174:175]
	v_lshlrev_b32_e32 v0, 16, v170
	v_pk_mul_f32 v[116:117], v[116:117], v[174:175]
	v_lshlrev_b32_e32 v174, 16, v192
	v_and_b32_e32 v175, 0xffff0000, v192
	v_pk_mul_f32 v[174:175], v[178:179], v[174:175]
	v_pk_mul_f32 v[110:111], v[110:111], v[174:175]
	v_lshlrev_b32_e32 v174, 16, v193
	v_and_b32_e32 v175, 0xffff0000, v193
	v_pk_mul_f32 v[174:175], v[180:181], v[174:175]
	v_max_f32_e32 v0, 0xda24260, v0
	v_pk_mul_f32 v[112:113], v[112:113], v[174:175]
	v_rcp_f32_e32 v174, v0
	v_and_b32_e32 v0, 0xffff0000, v170
	v_max_f32_e32 v0, 0xda24260, v0
	v_rcp_f32_e32 v175, v0
	v_lshlrev_b32_e32 v0, 16, v171
	v_max_f32_e32 v0, 0xda24260, v0
	v_rcp_f32_e32 v170, v0
	v_and_b32_e32 v0, 0xffff0000, v171
	v_max_f32_e32 v0, 0xda24260, v0
	v_rcp_f32_e32 v171, v0
	v_lshlrev_b32_e32 v0, 16, v172
	v_max_f32_e32 v0, 0xda24260, v0
	v_rcp_f32_e32 v176, v0
	v_and_b32_e32 v0, 0xffff0000, v172
	v_max_f32_e32 v0, 0xda24260, v0
	v_rcp_f32_e32 v177, v0
	v_lshlrev_b32_e32 v0, 16, v173
	v_max_f32_e32 v0, 0xda24260, v0
	v_rcp_f32_e32 v172, v0
	v_and_b32_e32 v0, 0xffff0000, v173
	v_max_f32_e32 v0, 0xda24260, v0
	v_lshlrev_b32_e32 v178, 16, v166
	v_and_b32_e32 v179, 0xffff0000, v166
	v_lshlrev_b32_e32 v166, 16, v167
	v_and_b32_e32 v167, 0xffff0000, v167
	v_rcp_f32_e32 v173, v0
	v_pk_mul_f32 v[166:167], v[170:171], v[166:167]
	v_lshlrev_b32_e32 v0, 16, v162
	v_pk_mul_f32 v[108:109], v[108:109], v[166:167]
	v_lshlrev_b32_e32 v166, 16, v168
	v_and_b32_e32 v167, 0xffff0000, v168
	v_pk_mul_f32 v[166:167], v[176:177], v[166:167]
	v_pk_mul_f32 v[102:103], v[102:103], v[166:167]
	v_lshlrev_b32_e32 v166, 16, v169
	v_and_b32_e32 v167, 0xffff0000, v169
	v_pk_mul_f32 v[166:167], v[172:173], v[166:167]
	v_max_f32_e32 v0, 0xda24260, v0
	v_pk_mul_f32 v[104:105], v[104:105], v[166:167]
	v_rcp_f32_e32 v166, v0
	v_and_b32_e32 v0, 0xffff0000, v162
	v_max_f32_e32 v0, 0xda24260, v0
	v_rcp_f32_e32 v167, v0
	v_lshlrev_b32_e32 v0, 16, v163
	v_max_f32_e32 v0, 0xda24260, v0
	v_rcp_f32_e32 v162, v0
	v_and_b32_e32 v0, 0xffff0000, v163
	v_max_f32_e32 v0, 0xda24260, v0
	v_rcp_f32_e32 v163, v0
	v_lshlrev_b32_e32 v0, 16, v164
	v_max_f32_e32 v0, 0xda24260, v0
	v_rcp_f32_e32 v168, v0
	v_and_b32_e32 v0, 0xffff0000, v164
	v_max_f32_e32 v0, 0xda24260, v0
	v_rcp_f32_e32 v169, v0
	v_lshlrev_b32_e32 v0, 16, v165
	v_max_f32_e32 v0, 0xda24260, v0
	v_rcp_f32_e32 v164, v0
	v_and_b32_e32 v0, 0xffff0000, v165
	v_max_f32_e32 v0, 0xda24260, v0
	v_lshlrev_b32_e32 v170, 16, v158
	v_and_b32_e32 v171, 0xffff0000, v158
	v_lshlrev_b32_e32 v158, 16, v159
	v_and_b32_e32 v159, 0xffff0000, v159
	v_rcp_f32_e32 v165, v0
	v_pk_mul_f32 v[158:159], v[162:163], v[158:159]
	v_lshlrev_b32_e32 v0, 16, v154
	v_pk_mul_f32 v[100:101], v[100:101], v[158:159]
	v_lshlrev_b32_e32 v158, 16, v160
	v_and_b32_e32 v159, 0xffff0000, v160
	v_pk_mul_f32 v[158:159], v[168:169], v[158:159]
	v_pk_mul_f32 v[90:91], v[90:91], v[158:159]
	v_lshlrev_b32_e32 v158, 16, v161
	v_and_b32_e32 v159, 0xffff0000, v161
	v_pk_mul_f32 v[158:159], v[164:165], v[158:159]
	v_max_f32_e32 v0, 0xda24260, v0
	v_pk_mul_f32 v[92:93], v[92:93], v[158:159]
	v_rcp_f32_e32 v158, v0
	v_and_b32_e32 v0, 0xffff0000, v154
	v_max_f32_e32 v0, 0xda24260, v0
	v_rcp_f32_e32 v159, v0
	v_lshlrev_b32_e32 v0, 16, v155
	v_max_f32_e32 v0, 0xda24260, v0
	v_rcp_f32_e32 v154, v0
	v_and_b32_e32 v0, 0xffff0000, v155
	v_max_f32_e32 v0, 0xda24260, v0
	v_rcp_f32_e32 v155, v0
	v_lshlrev_b32_e32 v0, 16, v156
	v_max_f32_e32 v0, 0xda24260, v0
	v_rcp_f32_e32 v160, v0
	v_and_b32_e32 v0, 0xffff0000, v156
	v_max_f32_e32 v0, 0xda24260, v0
	v_rcp_f32_e32 v161, v0
	v_lshlrev_b32_e32 v0, 16, v157
	v_max_f32_e32 v0, 0xda24260, v0
	v_rcp_f32_e32 v156, v0
	v_and_b32_e32 v0, 0xffff0000, v157
	v_max_f32_e32 v0, 0xda24260, v0
	v_lshlrev_b32_e32 v162, 16, v150
	v_and_b32_e32 v163, 0xffff0000, v150
	v_lshlrev_b32_e32 v150, 16, v151
	v_and_b32_e32 v151, 0xffff0000, v151
	v_rcp_f32_e32 v157, v0
	v_pk_mul_f32 v[150:151], v[154:155], v[150:151]
	v_lshlrev_b32_e32 v0, 16, v146
	v_pk_mul_f32 v[88:89], v[88:89], v[150:151]
	v_lshlrev_b32_e32 v150, 16, v152
	v_and_b32_e32 v151, 0xffff0000, v152
	v_pk_mul_f32 v[150:151], v[160:161], v[150:151]
	v_pk_mul_f32 v[82:83], v[82:83], v[150:151]
	v_lshlrev_b32_e32 v150, 16, v153
	v_and_b32_e32 v151, 0xffff0000, v153
	v_pk_mul_f32 v[150:151], v[156:157], v[150:151]
	v_max_f32_e32 v0, 0xda24260, v0
	v_pk_mul_f32 v[84:85], v[84:85], v[150:151]
	v_rcp_f32_e32 v150, v0
	v_and_b32_e32 v0, 0xffff0000, v146
	v_max_f32_e32 v0, 0xda24260, v0
	v_rcp_f32_e32 v151, v0
	v_lshlrev_b32_e32 v0, 16, v147
	v_max_f32_e32 v0, 0xda24260, v0
	v_rcp_f32_e32 v146, v0
	v_and_b32_e32 v0, 0xffff0000, v147
	v_max_f32_e32 v0, 0xda24260, v0
	v_rcp_f32_e32 v147, v0
	v_lshlrev_b32_e32 v0, 16, v148
	v_max_f32_e32 v0, 0xda24260, v0
	v_rcp_f32_e32 v152, v0
	v_and_b32_e32 v0, 0xffff0000, v148
	v_max_f32_e32 v0, 0xda24260, v0
	v_rcp_f32_e32 v153, v0
	v_lshlrev_b32_e32 v0, 16, v149
	v_max_f32_e32 v0, 0xda24260, v0
	v_rcp_f32_e32 v148, v0
	v_and_b32_e32 v0, 0xffff0000, v149
	v_max_f32_e32 v0, 0xda24260, v0
	v_lshlrev_b32_e32 v154, 16, v142
	v_and_b32_e32 v155, 0xffff0000, v142
	v_lshlrev_b32_e32 v142, 16, v143
	v_and_b32_e32 v143, 0xffff0000, v143
	v_rcp_f32_e32 v149, v0
	v_pk_mul_f32 v[142:143], v[146:147], v[142:143]
	v_lshlrev_b32_e32 v0, 16, v138
	v_pk_mul_f32 v[80:81], v[80:81], v[142:143]
	v_lshlrev_b32_e32 v142, 16, v144
	v_and_b32_e32 v143, 0xffff0000, v144
	v_pk_mul_f32 v[142:143], v[152:153], v[142:143]
	v_pk_mul_f32 v[74:75], v[74:75], v[142:143]
	v_lshlrev_b32_e32 v142, 16, v145
	v_and_b32_e32 v143, 0xffff0000, v145
	v_pk_mul_f32 v[142:143], v[148:149], v[142:143]
	v_max_f32_e32 v0, 0xda24260, v0
	v_pk_mul_f32 v[76:77], v[76:77], v[142:143]
	v_rcp_f32_e32 v142, v0
	v_and_b32_e32 v0, 0xffff0000, v138
	v_max_f32_e32 v0, 0xda24260, v0
	v_rcp_f32_e32 v143, v0
	v_lshlrev_b32_e32 v0, 16, v139
	v_max_f32_e32 v0, 0xda24260, v0
	v_rcp_f32_e32 v138, v0
	v_and_b32_e32 v0, 0xffff0000, v139
	v_max_f32_e32 v0, 0xda24260, v0
	v_rcp_f32_e32 v139, v0
	v_lshlrev_b32_e32 v0, 16, v140
	v_max_f32_e32 v0, 0xda24260, v0
	v_rcp_f32_e32 v144, v0
	v_and_b32_e32 v0, 0xffff0000, v140
	v_max_f32_e32 v0, 0xda24260, v0
	v_rcp_f32_e32 v145, v0
	v_lshlrev_b32_e32 v0, 16, v141
	v_max_f32_e32 v0, 0xda24260, v0
	v_rcp_f32_e32 v140, v0
	v_and_b32_e32 v0, 0xffff0000, v141
	v_max_f32_e32 v0, 0xda24260, v0
	v_lshlrev_b32_e32 v146, 16, v134
	v_and_b32_e32 v147, 0xffff0000, v134
	v_lshlrev_b32_e32 v134, 16, v135
	v_and_b32_e32 v135, 0xffff0000, v135
	v_rcp_f32_e32 v141, v0
	v_pk_mul_f32 v[134:135], v[138:139], v[134:135]
	v_add_u32_e32 v0, 0x80, v236
	v_pk_mul_f32 v[72:73], v[72:73], v[134:135]
	v_lshlrev_b32_e32 v134, 16, v136
	v_and_b32_e32 v135, 0xffff0000, v136
	v_pk_mul_f32 v[134:135], v[144:145], v[134:135]
	v_ashrrev_i32_e32 v136, 11, v0
	v_pk_mul_f32 v[66:67], v[66:67], v[134:135]
	v_lshlrev_b32_e32 v134, 16, v137
	v_and_b32_e32 v135, 0xffff0000, v137
	v_lshlrev_b32_e32 v0, 10, v0
	v_pk_mul_f32 v[134:135], v[140:141], v[134:135]
	v_and_b32_e32 v0, 0x1ffc00, v0
	v_pk_mul_f32 v[68:69], v[68:69], v[134:135]
	v_lshl_add_u64 v[134:135], v[0:1], 0, v[220:221]
	v_mad_i64_i32 v[134:135], s[46:47], v136, s61, v[134:135]
	v_lshlrev_b64 v[134:135], 1, v[134:135]
	v_lshl_add_u64 v[136:137], s[4:5], 0, v[134:135]
	v_lshl_add_u64 v[134:135], s[10:11], 0, v[134:135]
	v_add_u32_e32 v0, 0x90, v236
	global_load_dwordx4 v[190:193], v[136:137], off
	global_load_dwordx4 v[194:197], v[134:135], off
	global_load_dwordx4 v[182:185], v[136:137], off offset:256
	global_load_dwordx4 v[186:189], v[134:135], off offset:256
	v_ashrrev_i32_e32 v136, 11, v0
	v_lshlrev_b32_e32 v0, 10, v0
	v_and_b32_e32 v0, 0x1ffc00, v0
	v_lshl_add_u64 v[134:135], v[0:1], 0, v[220:221]
	v_mad_i64_i32 v[134:135], s[46:47], v136, s61, v[134:135]
	v_lshlrev_b64 v[134:135], 1, v[134:135]
	v_pk_mul_f32 v[174:175], v[174:175], v[178:179]
	v_pk_mul_f32 v[166:167], v[166:167], v[170:171]
	v_lshl_add_u64 v[136:137], s[4:5], 0, v[134:135]
	v_lshl_add_u64 v[134:135], s[10:11], 0, v[134:135]
	v_add_u32_e32 v0, 0xa0, v236
	v_pk_mul_f32 v[106:107], v[106:107], v[174:175]
	v_pk_mul_f32 v[98:99], v[98:99], v[166:167]
	global_load_dwordx4 v[174:177], v[136:137], off
	global_load_dwordx4 v[178:181], v[134:135], off
	global_load_dwordx4 v[166:169], v[136:137], off offset:256
	global_load_dwordx4 v[170:173], v[134:135], off offset:256
	v_ashrrev_i32_e32 v136, 11, v0
	v_lshlrev_b32_e32 v0, 10, v0
	v_and_b32_e32 v0, 0x1ffc00, v0
	v_lshl_add_u64 v[134:135], v[0:1], 0, v[220:221]
	v_mad_i64_i32 v[134:135], s[46:47], v136, s61, v[134:135]
	v_lshlrev_b64 v[134:135], 1, v[134:135]
	v_pk_mul_f32 v[158:159], v[158:159], v[162:163]
	v_pk_mul_f32 v[150:151], v[150:151], v[154:155]
	v_lshl_add_u64 v[136:137], s[4:5], 0, v[134:135]
	v_lshl_add_u64 v[134:135], s[10:11], 0, v[134:135]
	v_add_u32_e32 v0, 0xb0, v236
	v_pk_mul_f32 v[86:87], v[86:87], v[158:159]
	v_pk_mul_f32 v[78:79], v[78:79], v[150:151]
	global_load_dwordx4 v[158:161], v[136:137], off
	global_load_dwordx4 v[162:165], v[134:135], off
	global_load_dwordx4 v[150:153], v[136:137], off offset:256
	global_load_dwordx4 v[154:157], v[134:135], off offset:256
	v_ashrrev_i32_e32 v136, 11, v0
	v_lshlrev_b32_e32 v0, 10, v0
	v_and_b32_e32 v0, 0x1ffc00, v0
	v_lshl_add_u64 v[134:135], v[0:1], 0, v[220:221]
	v_mad_i64_i32 v[134:135], s[46:47], v136, s61, v[134:135]
	v_lshlrev_b64 v[134:135], 1, v[134:135]
	v_pk_mul_f32 v[142:143], v[142:143], v[146:147]
	v_lshl_add_u64 v[136:137], s[4:5], 0, v[134:135]
	v_lshl_add_u64 v[138:139], s[10:11], 0, v[134:135]
	v_pk_mul_f32 v[70:71], v[70:71], v[142:143]
	global_load_dwordx4 v[142:145], v[136:137], off
	global_load_dwordx4 v[146:149], v[138:139], off
	s_nop 0
	global_load_dwordx4 v[134:137], v[136:137], off offset:256
	s_nop 0
	global_load_dwordx4 v[138:141], v[138:139], off offset:256
	v_pk_mul_f32 v[202:203], v[202:203], v[240:241]
	s_nop 0
	v_pk_mul_f32 v[130:131], v[130:131], v[202:203]
	s_waitcnt vmcnt(0)
	v_lshlrev_b32_e32 v0, 16, v194
	v_max_f32_e32 v0, 0xda24260, v0
	v_rcp_f32_e32 v202, v0
	v_and_b32_e32 v0, 0xffff0000, v194
	v_max_f32_e32 v0, 0xda24260, v0
	v_rcp_f32_e32 v203, v0
	v_lshlrev_b32_e32 v0, 16, v195
	v_max_f32_e32 v0, 0xda24260, v0
	v_rcp_f32_e32 v194, v0
	v_and_b32_e32 v0, 0xffff0000, v195
	v_max_f32_e32 v0, 0xda24260, v0
	v_rcp_f32_e32 v195, v0
	v_lshlrev_b32_e32 v0, 16, v196
	v_max_f32_e32 v0, 0xda24260, v0
	v_rcp_f32_e32 v220, v0
	v_and_b32_e32 v0, 0xffff0000, v196
	v_max_f32_e32 v0, 0xda24260, v0
	v_rcp_f32_e32 v221, v0
	v_lshlrev_b32_e32 v0, 16, v197
	v_max_f32_e32 v0, 0xda24260, v0
	v_rcp_f32_e32 v196, v0
	v_and_b32_e32 v0, 0xffff0000, v197
	v_max_f32_e32 v0, 0xda24260, v0
	v_lshlrev_b32_e32 v236, 16, v190
	v_and_b32_e32 v237, 0xffff0000, v190
	v_lshlrev_b32_e32 v190, 16, v191
	v_and_b32_e32 v191, 0xffff0000, v191
	v_rcp_f32_e32 v197, v0
	v_pk_mul_f32 v[190:191], v[194:195], v[190:191]
	v_lshlrev_b32_e32 v0, 16, v186
	v_pk_mul_f32 v[64:65], v[64:65], v[190:191]
	v_lshlrev_b32_e32 v190, 16, v192
	v_and_b32_e32 v191, 0xffff0000, v192
	v_pk_mul_f32 v[190:191], v[220:221], v[190:191]
	v_pk_mul_f32 v[58:59], v[58:59], v[190:191]
	v_lshlrev_b32_e32 v190, 16, v193
	v_and_b32_e32 v191, 0xffff0000, v193
	v_pk_mul_f32 v[190:191], v[196:197], v[190:191]
	v_max_f32_e32 v0, 0xda24260, v0
	v_pk_mul_f32 v[60:61], v[60:61], v[190:191]
	v_rcp_f32_e32 v190, v0
	v_and_b32_e32 v0, 0xffff0000, v186
	v_max_f32_e32 v0, 0xda24260, v0
	v_rcp_f32_e32 v191, v0
	v_lshlrev_b32_e32 v0, 16, v187
	v_max_f32_e32 v0, 0xda24260, v0
	v_rcp_f32_e32 v186, v0
	v_and_b32_e32 v0, 0xffff0000, v187
	v_max_f32_e32 v0, 0xda24260, v0
	v_rcp_f32_e32 v187, v0
	v_lshlrev_b32_e32 v0, 16, v188
	v_max_f32_e32 v0, 0xda24260, v0
	v_rcp_f32_e32 v192, v0
	v_and_b32_e32 v0, 0xffff0000, v188
	v_max_f32_e32 v0, 0xda24260, v0
	v_rcp_f32_e32 v193, v0
	v_lshlrev_b32_e32 v0, 16, v189
	v_max_f32_e32 v0, 0xda24260, v0
	v_rcp_f32_e32 v188, v0
	v_and_b32_e32 v0, 0xffff0000, v189
	v_max_f32_e32 v0, 0xda24260, v0
	v_lshlrev_b32_e32 v194, 16, v182
	v_and_b32_e32 v195, 0xffff0000, v182
	v_lshlrev_b32_e32 v182, 16, v183
	v_and_b32_e32 v183, 0xffff0000, v183
	v_rcp_f32_e32 v189, v0
	v_pk_mul_f32 v[182:183], v[186:187], v[182:183]
	v_lshlrev_b32_e32 v0, 16, v178
	v_pk_mul_f32 v[56:57], v[56:57], v[182:183]
	v_lshlrev_b32_e32 v182, 16, v184
	v_and_b32_e32 v183, 0xffff0000, v184
	v_pk_mul_f32 v[182:183], v[192:193], v[182:183]
	v_pk_mul_f32 v[50:51], v[50:51], v[182:183]
	v_lshlrev_b32_e32 v182, 16, v185
	v_and_b32_e32 v183, 0xffff0000, v185
	v_pk_mul_f32 v[182:183], v[188:189], v[182:183]
	v_max_f32_e32 v0, 0xda24260, v0
	v_pk_mul_f32 v[52:53], v[52:53], v[182:183]
	v_rcp_f32_e32 v182, v0
	v_and_b32_e32 v0, 0xffff0000, v178
	v_max_f32_e32 v0, 0xda24260, v0
	v_rcp_f32_e32 v183, v0
	v_lshlrev_b32_e32 v0, 16, v179
	v_max_f32_e32 v0, 0xda24260, v0
	v_rcp_f32_e32 v178, v0
	v_and_b32_e32 v0, 0xffff0000, v179
	v_max_f32_e32 v0, 0xda24260, v0
	v_rcp_f32_e32 v179, v0
	v_lshlrev_b32_e32 v0, 16, v180
	v_max_f32_e32 v0, 0xda24260, v0
	v_rcp_f32_e32 v184, v0
	v_and_b32_e32 v0, 0xffff0000, v180
	v_max_f32_e32 v0, 0xda24260, v0
	v_rcp_f32_e32 v185, v0
	v_lshlrev_b32_e32 v0, 16, v181
	v_max_f32_e32 v0, 0xda24260, v0
	v_rcp_f32_e32 v180, v0
	v_and_b32_e32 v0, 0xffff0000, v181
	v_max_f32_e32 v0, 0xda24260, v0
	v_lshlrev_b32_e32 v186, 16, v174
	v_and_b32_e32 v187, 0xffff0000, v174
	v_lshlrev_b32_e32 v174, 16, v175
	v_and_b32_e32 v175, 0xffff0000, v175
	v_rcp_f32_e32 v181, v0
	v_pk_mul_f32 v[174:175], v[178:179], v[174:175]
	v_lshlrev_b32_e32 v0, 16, v170
	v_pk_mul_f32 v[48:49], v[48:49], v[174:175]
	v_lshlrev_b32_e32 v174, 16, v176
	v_and_b32_e32 v175, 0xffff0000, v176
	v_pk_mul_f32 v[174:175], v[184:185], v[174:175]
	v_pk_mul_f32 v[42:43], v[42:43], v[174:175]
	v_lshlrev_b32_e32 v174, 16, v177
	v_and_b32_e32 v175, 0xffff0000, v177
	v_pk_mul_f32 v[174:175], v[180:181], v[174:175]
	v_max_f32_e32 v0, 0xda24260, v0
	v_pk_mul_f32 v[44:45], v[44:45], v[174:175]
	v_rcp_f32_e32 v174, v0
	v_and_b32_e32 v0, 0xffff0000, v170
	v_max_f32_e32 v0, 0xda24260, v0
	v_rcp_f32_e32 v175, v0
	v_lshlrev_b32_e32 v0, 16, v171
	v_max_f32_e32 v0, 0xda24260, v0
	v_rcp_f32_e32 v170, v0
	v_and_b32_e32 v0, 0xffff0000, v171
	v_max_f32_e32 v0, 0xda24260, v0
	v_rcp_f32_e32 v171, v0
	v_lshlrev_b32_e32 v0, 16, v172
	v_max_f32_e32 v0, 0xda24260, v0
	v_rcp_f32_e32 v176, v0
	v_and_b32_e32 v0, 0xffff0000, v172
	v_max_f32_e32 v0, 0xda24260, v0
	v_rcp_f32_e32 v177, v0
	v_lshlrev_b32_e32 v0, 16, v173
	v_max_f32_e32 v0, 0xda24260, v0
	v_rcp_f32_e32 v172, v0
	v_and_b32_e32 v0, 0xffff0000, v173
	v_max_f32_e32 v0, 0xda24260, v0
	v_lshlrev_b32_e32 v178, 16, v166
	v_and_b32_e32 v179, 0xffff0000, v166
	v_lshlrev_b32_e32 v166, 16, v167
	v_and_b32_e32 v167, 0xffff0000, v167
	v_rcp_f32_e32 v173, v0
	v_pk_mul_f32 v[166:167], v[170:171], v[166:167]
	v_lshlrev_b32_e32 v0, 16, v162
	v_pk_mul_f32 v[40:41], v[40:41], v[166:167]
	v_lshlrev_b32_e32 v166, 16, v168
	v_and_b32_e32 v167, 0xffff0000, v168
	v_pk_mul_f32 v[166:167], v[176:177], v[166:167]
	v_pk_mul_f32 v[34:35], v[34:35], v[166:167]
	v_lshlrev_b32_e32 v166, 16, v169
	v_and_b32_e32 v167, 0xffff0000, v169
	v_pk_mul_f32 v[166:167], v[172:173], v[166:167]
	v_max_f32_e32 v0, 0xda24260, v0
	v_pk_mul_f32 v[36:37], v[36:37], v[166:167]
	v_rcp_f32_e32 v166, v0
	v_and_b32_e32 v0, 0xffff0000, v162
	v_max_f32_e32 v0, 0xda24260, v0
	v_rcp_f32_e32 v167, v0
	v_lshlrev_b32_e32 v0, 16, v163
	v_max_f32_e32 v0, 0xda24260, v0
	v_rcp_f32_e32 v162, v0
	v_and_b32_e32 v0, 0xffff0000, v163
	v_max_f32_e32 v0, 0xda24260, v0
	v_rcp_f32_e32 v163, v0
	v_lshlrev_b32_e32 v0, 16, v164
	v_max_f32_e32 v0, 0xda24260, v0
	v_rcp_f32_e32 v168, v0
	v_and_b32_e32 v0, 0xffff0000, v164
	v_max_f32_e32 v0, 0xda24260, v0
	v_rcp_f32_e32 v169, v0
	v_lshlrev_b32_e32 v0, 16, v165
	v_max_f32_e32 v0, 0xda24260, v0
	v_rcp_f32_e32 v164, v0
	v_and_b32_e32 v0, 0xffff0000, v165
	v_max_f32_e32 v0, 0xda24260, v0
	v_lshlrev_b32_e32 v170, 16, v158
	v_and_b32_e32 v171, 0xffff0000, v158
	v_lshlrev_b32_e32 v158, 16, v159
	v_and_b32_e32 v159, 0xffff0000, v159
	v_rcp_f32_e32 v165, v0
	v_pk_mul_f32 v[158:159], v[162:163], v[158:159]
	v_lshlrev_b32_e32 v0, 16, v154
	v_pk_mul_f32 v[32:33], v[32:33], v[158:159]
	v_lshlrev_b32_e32 v158, 16, v160
	v_and_b32_e32 v159, 0xffff0000, v160
	v_pk_mul_f32 v[158:159], v[168:169], v[158:159]
	v_pk_mul_f32 v[26:27], v[26:27], v[158:159]
	v_lshlrev_b32_e32 v158, 16, v161
	v_and_b32_e32 v159, 0xffff0000, v161
	v_pk_mul_f32 v[158:159], v[164:165], v[158:159]
	v_max_f32_e32 v0, 0xda24260, v0
	v_pk_mul_f32 v[28:29], v[28:29], v[158:159]
	v_rcp_f32_e32 v158, v0
	v_and_b32_e32 v0, 0xffff0000, v154
	v_max_f32_e32 v0, 0xda24260, v0
	v_rcp_f32_e32 v159, v0
	v_lshlrev_b32_e32 v0, 16, v155
	v_max_f32_e32 v0, 0xda24260, v0
	v_rcp_f32_e32 v154, v0
	v_and_b32_e32 v0, 0xffff0000, v155
	v_max_f32_e32 v0, 0xda24260, v0
	v_rcp_f32_e32 v155, v0
	v_lshlrev_b32_e32 v0, 16, v156
	v_max_f32_e32 v0, 0xda24260, v0
	v_rcp_f32_e32 v160, v0
	v_and_b32_e32 v0, 0xffff0000, v156
	v_max_f32_e32 v0, 0xda24260, v0
	v_rcp_f32_e32 v161, v0
	v_lshlrev_b32_e32 v0, 16, v157
	v_max_f32_e32 v0, 0xda24260, v0
	v_rcp_f32_e32 v156, v0
	v_and_b32_e32 v0, 0xffff0000, v157
	v_max_f32_e32 v0, 0xda24260, v0
	v_lshlrev_b32_e32 v162, 16, v150
	v_and_b32_e32 v163, 0xffff0000, v150
	v_lshlrev_b32_e32 v150, 16, v151
	v_and_b32_e32 v151, 0xffff0000, v151
	v_rcp_f32_e32 v157, v0
	v_pk_mul_f32 v[150:151], v[154:155], v[150:151]
	v_lshlrev_b32_e32 v0, 16, v146
	v_pk_mul_f32 v[24:25], v[24:25], v[150:151]
	v_lshlrev_b32_e32 v150, 16, v152
	v_and_b32_e32 v151, 0xffff0000, v152
	v_pk_mul_f32 v[150:151], v[160:161], v[150:151]
	v_pk_mul_f32 v[18:19], v[18:19], v[150:151]
	v_lshlrev_b32_e32 v150, 16, v153
	v_and_b32_e32 v151, 0xffff0000, v153
	v_pk_mul_f32 v[150:151], v[156:157], v[150:151]
	v_max_f32_e32 v0, 0xda24260, v0
	v_pk_mul_f32 v[20:21], v[20:21], v[150:151]
	v_rcp_f32_e32 v150, v0
	v_and_b32_e32 v0, 0xffff0000, v146
	v_max_f32_e32 v0, 0xda24260, v0
	v_rcp_f32_e32 v151, v0
	v_lshlrev_b32_e32 v0, 16, v147
	v_max_f32_e32 v0, 0xda24260, v0
	v_rcp_f32_e32 v146, v0
	v_and_b32_e32 v0, 0xffff0000, v147
	v_max_f32_e32 v0, 0xda24260, v0
	v_rcp_f32_e32 v147, v0
	v_lshlrev_b32_e32 v0, 16, v148
	v_max_f32_e32 v0, 0xda24260, v0
	v_rcp_f32_e32 v152, v0
	v_and_b32_e32 v0, 0xffff0000, v148
	v_max_f32_e32 v0, 0xda24260, v0
	v_rcp_f32_e32 v153, v0
	v_lshlrev_b32_e32 v0, 16, v149
	v_max_f32_e32 v0, 0xda24260, v0
	v_rcp_f32_e32 v148, v0
	v_and_b32_e32 v0, 0xffff0000, v149
	v_max_f32_e32 v0, 0xda24260, v0
	v_lshlrev_b32_e32 v154, 16, v142
	v_and_b32_e32 v155, 0xffff0000, v142
	v_lshlrev_b32_e32 v142, 16, v143
	v_and_b32_e32 v143, 0xffff0000, v143
	v_rcp_f32_e32 v149, v0
	v_pk_mul_f32 v[142:143], v[146:147], v[142:143]
	v_lshlrev_b32_e32 v0, 16, v138
	v_pk_mul_f32 v[16:17], v[16:17], v[142:143]
	v_lshlrev_b32_e32 v142, 16, v144
	v_and_b32_e32 v143, 0xffff0000, v144
	v_pk_mul_f32 v[142:143], v[152:153], v[142:143]
	v_pk_mul_f32 v[10:11], v[10:11], v[142:143]
	v_lshlrev_b32_e32 v142, 16, v145
	v_and_b32_e32 v143, 0xffff0000, v145
	v_pk_mul_f32 v[142:143], v[148:149], v[142:143]
	v_max_f32_e32 v0, 0xda24260, v0
	v_pk_mul_f32 v[12:13], v[12:13], v[142:143]
	v_rcp_f32_e32 v142, v0
	v_and_b32_e32 v0, 0xffff0000, v138
	v_max_f32_e32 v0, 0xda24260, v0
	v_rcp_f32_e32 v143, v0
	v_lshlrev_b32_e32 v0, 16, v139
	v_max_f32_e32 v0, 0xda24260, v0
	v_rcp_f32_e32 v138, v0
	v_and_b32_e32 v0, 0xffff0000, v139
	v_max_f32_e32 v0, 0xda24260, v0
	v_rcp_f32_e32 v139, v0
	v_lshlrev_b32_e32 v0, 16, v140
	v_max_f32_e32 v0, 0xda24260, v0
	v_rcp_f32_e32 v144, v0
	v_and_b32_e32 v0, 0xffff0000, v140
	v_max_f32_e32 v0, 0xda24260, v0
	v_rcp_f32_e32 v145, v0
	v_lshlrev_b32_e32 v0, 16, v141
	v_max_f32_e32 v0, 0xda24260, v0
	v_rcp_f32_e32 v140, v0
	v_and_b32_e32 v0, 0xffff0000, v141
	v_max_f32_e32 v0, 0xda24260, v0
	v_lshlrev_b32_e32 v146, 16, v134
	v_and_b32_e32 v147, 0xffff0000, v134
	v_lshlrev_b32_e32 v134, 16, v135
	v_and_b32_e32 v135, 0xffff0000, v135
	v_rcp_f32_e32 v141, v0
	v_pk_mul_f32 v[134:135], v[138:139], v[134:135]
	v_pk_mul_f32 v[202:203], v[202:203], v[236:237]
	v_pk_mul_f32 v[8:9], v[8:9], v[134:135]
	v_lshlrev_b32_e32 v134, 16, v136
	v_and_b32_e32 v135, 0xffff0000, v136
	v_pk_mul_f32 v[134:135], v[144:145], v[134:135]
	v_pk_mul_f32 v[190:191], v[190:191], v[194:195]
	v_pk_mul_f32 v[2:3], v[2:3], v[134:135]
	v_lshlrev_b32_e32 v134, 16, v137
	v_and_b32_e32 v135, 0xffff0000, v137
	v_pk_mul_f32 v[182:183], v[182:183], v[186:187]
	v_pk_mul_f32 v[174:175], v[174:175], v[178:179]
	v_pk_mul_f32 v[166:167], v[166:167], v[170:171]
	v_pk_mul_f32 v[158:159], v[158:159], v[162:163]
	v_pk_mul_f32 v[150:151], v[150:151], v[154:155]
	v_pk_mul_f32 v[142:143], v[142:143], v[146:147]
	v_pk_mul_f32 v[134:135], v[140:141], v[134:135]
	v_pk_mul_f32 v[62:63], v[62:63], v[202:203]
	v_pk_mul_f32 v[54:55], v[54:55], v[190:191]
	v_pk_mul_f32 v[46:47], v[46:47], v[182:183]
	v_pk_mul_f32 v[38:39], v[38:39], v[174:175]
	v_pk_mul_f32 v[30:31], v[30:31], v[166:167]
	v_pk_mul_f32 v[22:23], v[22:23], v[158:159]
	v_pk_mul_f32 v[14:15], v[14:15], v[150:151]
	v_pk_mul_f32 v[6:7], v[6:7], v[142:143]
	v_pk_mul_f32 v[4:5], v[4:5], v[134:135]
	s_branch .LBB0_44

.LBB0_49:
	s_waitcnt vmcnt(0)
	v_lshlrev_b32_e32 v202, 16, v214
	v_and_b32_e32 v203, 0xffff0000, v214
	v_max_f32_e32 v202, 0xda24260, v202
	v_max_f32_e32 v203, 0xda24260, v203
	v_pk_mul_f32 v[130:131], v[130:131], v[202:203]
	v_lshlrev_b32_e32 v202, 16, v215
	v_and_b32_e32 v203, 0xffff0000, v215
	v_max_f32_e32 v202, 0xda24260, v202
	v_max_f32_e32 v203, 0xda24260, v203
	v_pk_mul_f32 v[132:133], v[132:133], v[202:203]
	v_lshlrev_b32_e32 v202, 16, v216
	v_and_b32_e32 v203, 0xffff0000, v216
	v_max_f32_e32 v202, 0xda24260, v202
	v_max_f32_e32 v203, 0xda24260, v203
	v_pk_mul_f32 v[202:203], v[126:127], v[202:203]
	v_lshlrev_b32_e32 v126, 16, v217
	v_and_b32_e32 v127, 0xffff0000, v217
	s_add_u32 s42, s18, s23
	v_max_f32_e32 v126, 0xda24260, v126
	v_max_f32_e32 v127, 0xda24260, v127
	s_addc_u32 s43, s19, s31
	v_pk_mul_f32 v[214:215], v[128:129], v[126:127]
	v_cvt_pk_bf16_f32 v126, v130, v131
	v_lshl_add_u64 v[130:131], s[42:43], 0, v[0:1]
	v_lshlrev_b32_e32 v0, 16, v218
	v_cvt_pk_bf16_f32 v127, v132, v133
	v_cvt_pk_bf16_f32 v128, v202, v203
	v_cvt_pk_bf16_f32 v129, v214, v215
	v_lshl_add_u64 v[130:131], v[130:131], 0, v[182:183]
	global_store_dwordx4 v[130:131], v[126:129], off
	s_andn2_b64 vcc, exec, s[36:37]
	s_mov_b64 s[36:37], -1
	v_max_f32_e32 v126, 0xda24260, v0
	v_and_b32_e32 v0, 0xffff0000, v218
	v_max_f32_e32 v127, 0xda24260, v0
	v_lshlrev_b32_e32 v0, 16, v219
	v_pk_mul_f32 v[122:123], v[122:123], v[126:127]
	v_max_f32_e32 v126, 0xda24260, v0
	v_and_b32_e32 v0, 0xffff0000, v219
	v_max_f32_e32 v127, 0xda24260, v0
	v_lshlrev_b32_e32 v0, 16, v220
	v_pk_mul_f32 v[124:125], v[124:125], v[126:127]
	v_max_f32_e32 v126, 0xda24260, v0
	v_and_b32_e32 v0, 0xffff0000, v220
	v_max_f32_e32 v127, 0xda24260, v0
	v_lshlrev_b32_e32 v0, 16, v221
	v_pk_mul_f32 v[126:127], v[118:119], v[126:127]
	v_max_f32_e32 v118, 0xda24260, v0
	v_and_b32_e32 v0, 0xffff0000, v221
	v_max_f32_e32 v119, 0xda24260, v0
	v_pk_mul_f32 v[128:129], v[120:121], v[118:119]
	v_lshlrev_b32_e32 v0, 16, v236
	v_cvt_pk_bf16_f32 v118, v122, v123
	v_cvt_pk_bf16_f32 v119, v124, v125
	v_cvt_pk_bf16_f32 v120, v126, v127
	v_cvt_pk_bf16_f32 v121, v128, v129
	global_store_dwordx4 v[130:131], v[118:121], off offset:256
	s_nop 1
	v_max_f32_e32 v118, 0xda24260, v0
	v_and_b32_e32 v0, 0xffff0000, v236
	v_max_f32_e32 v119, 0xda24260, v0
	v_lshlrev_b32_e32 v0, 16, v237
	v_pk_mul_f32 v[114:115], v[114:115], v[118:119]
	v_max_f32_e32 v118, 0xda24260, v0
	v_and_b32_e32 v0, 0xffff0000, v237
	v_max_f32_e32 v119, 0xda24260, v0
	v_lshlrev_b32_e32 v0, 16, v238
	v_pk_mul_f32 v[116:117], v[116:117], v[118:119]
	v_max_f32_e32 v118, 0xda24260, v0
	v_and_b32_e32 v0, 0xffff0000, v238
	v_max_f32_e32 v119, 0xda24260, v0
	v_lshlrev_b32_e32 v0, 16, v239
	v_pk_mul_f32 v[118:119], v[110:111], v[118:119]
	v_max_f32_e32 v110, 0xda24260, v0
	v_and_b32_e32 v0, 0xffff0000, v239
	v_max_f32_e32 v111, 0xda24260, v0
	v_pk_mul_f32 v[120:121], v[112:113], v[110:111]
	v_cvt_pk_bf16_f32 v110, v114, v115
	v_lshl_add_u64 v[114:115], s[42:43], 0, v[196:197]
	v_lshlrev_b32_e32 v0, 16, v240
	v_cvt_pk_bf16_f32 v111, v116, v117
	v_cvt_pk_bf16_f32 v112, v118, v119
	v_cvt_pk_bf16_f32 v113, v120, v121
	v_lshl_add_u64 v[114:115], v[114:115], 0, v[182:183]
	global_store_dwordx4 v[114:115], v[110:113], off
	s_nop 1
	v_max_f32_e32 v110, 0xda24260, v0
	v_and_b32_e32 v0, 0xffff0000, v240
	v_max_f32_e32 v111, 0xda24260, v0
	v_lshlrev_b32_e32 v0, 16, v241
	v_pk_mul_f32 v[106:107], v[106:107], v[110:111]
	v_max_f32_e32 v110, 0xda24260, v0
	v_and_b32_e32 v0, 0xffff0000, v241
	v_max_f32_e32 v111, 0xda24260, v0
	v_lshlrev_b32_e32 v0, 16, v242
	v_pk_mul_f32 v[108:109], v[108:109], v[110:111]
	v_max_f32_e32 v110, 0xda24260, v0
	v_and_b32_e32 v0, 0xffff0000, v242
	v_max_f32_e32 v111, 0xda24260, v0
	v_lshlrev_b32_e32 v0, 16, v243
	v_pk_mul_f32 v[110:111], v[102:103], v[110:111]
	v_max_f32_e32 v102, 0xda24260, v0
	v_and_b32_e32 v0, 0xffff0000, v243
	v_max_f32_e32 v103, 0xda24260, v0
	v_pk_mul_f32 v[112:113], v[104:105], v[102:103]
	v_lshlrev_b32_e32 v0, 16, v178
	v_cvt_pk_bf16_f32 v102, v106, v107
	v_cvt_pk_bf16_f32 v103, v108, v109
	v_cvt_pk_bf16_f32 v104, v110, v111
	v_cvt_pk_bf16_f32 v105, v112, v113
	global_store_dwordx4 v[114:115], v[102:105], off offset:256
	s_nop 1
	v_max_f32_e32 v102, 0xda24260, v0
	v_and_b32_e32 v0, 0xffff0000, v178
	v_max_f32_e32 v103, 0xda24260, v0
	v_lshlrev_b32_e32 v0, 16, v179
	v_pk_mul_f32 v[98:99], v[98:99], v[102:103]
	v_max_f32_e32 v102, 0xda24260, v0
	v_and_b32_e32 v0, 0xffff0000, v179
	v_max_f32_e32 v103, 0xda24260, v0
	v_lshlrev_b32_e32 v0, 16, v180
	v_pk_mul_f32 v[100:101], v[100:101], v[102:103]
	v_max_f32_e32 v102, 0xda24260, v0
	v_and_b32_e32 v0, 0xffff0000, v180
	v_max_f32_e32 v103, 0xda24260, v0
	v_lshlrev_b32_e32 v0, 16, v181
	v_pk_mul_f32 v[102:103], v[90:91], v[102:103]
	v_max_f32_e32 v90, 0xda24260, v0
	v_and_b32_e32 v0, 0xffff0000, v181
	v_max_f32_e32 v91, 0xda24260, v0
	v_pk_mul_f32 v[104:105], v[92:93], v[90:91]
	v_cvt_pk_bf16_f32 v90, v98, v99
	v_lshl_add_u64 v[98:99], s[42:43], 0, v[194:195]
	v_lshlrev_b32_e32 v0, 16, v174
	v_cvt_pk_bf16_f32 v91, v100, v101
	v_cvt_pk_bf16_f32 v92, v102, v103
	v_cvt_pk_bf16_f32 v93, v104, v105
	v_lshl_add_u64 v[98:99], v[98:99], 0, v[182:183]
	global_store_dwordx4 v[98:99], v[90:93], off
	s_nop 1
	v_max_f32_e32 v90, 0xda24260, v0
	v_and_b32_e32 v0, 0xffff0000, v174
	v_max_f32_e32 v91, 0xda24260, v0
	v_lshlrev_b32_e32 v0, 16, v175
	v_pk_mul_f32 v[86:87], v[86:87], v[90:91]
	v_max_f32_e32 v90, 0xda24260, v0
	v_and_b32_e32 v0, 0xffff0000, v175
	v_max_f32_e32 v91, 0xda24260, v0
	v_lshlrev_b32_e32 v0, 16, v176
	v_pk_mul_f32 v[88:89], v[88:89], v[90:91]
	v_max_f32_e32 v90, 0xda24260, v0
	v_and_b32_e32 v0, 0xffff0000, v176
	v_max_f32_e32 v91, 0xda24260, v0
	v_lshlrev_b32_e32 v0, 16, v177
	v_pk_mul_f32 v[90:91], v[82:83], v[90:91]
	v_max_f32_e32 v82, 0xda24260, v0
	v_and_b32_e32 v0, 0xffff0000, v177
	v_max_f32_e32 v83, 0xda24260, v0
	v_pk_mul_f32 v[92:93], v[84:85], v[82:83]
	v_lshlrev_b32_e32 v0, 16, v170
	v_cvt_pk_bf16_f32 v82, v86, v87
	v_cvt_pk_bf16_f32 v83, v88, v89
	v_cvt_pk_bf16_f32 v84, v90, v91
	v_cvt_pk_bf16_f32 v85, v92, v93
	global_store_dwordx4 v[98:99], v[82:85], off offset:256
	s_nop 1
	v_max_f32_e32 v82, 0xda24260, v0
	v_and_b32_e32 v0, 0xffff0000, v170
	v_max_f32_e32 v83, 0xda24260, v0
	v_lshlrev_b32_e32 v0, 16, v171
	v_pk_mul_f32 v[78:79], v[78:79], v[82:83]
	v_max_f32_e32 v82, 0xda24260, v0
	v_and_b32_e32 v0, 0xffff0000, v171
	v_max_f32_e32 v83, 0xda24260, v0
	v_lshlrev_b32_e32 v0, 16, v172
	v_pk_mul_f32 v[80:81], v[80:81], v[82:83]
	v_max_f32_e32 v82, 0xda24260, v0
	v_and_b32_e32 v0, 0xffff0000, v172
	v_max_f32_e32 v83, 0xda24260, v0
	v_lshlrev_b32_e32 v0, 16, v173
	v_pk_mul_f32 v[82:83], v[74:75], v[82:83]
	v_max_f32_e32 v74, 0xda24260, v0
	v_and_b32_e32 v0, 0xffff0000, v173
	v_max_f32_e32 v75, 0xda24260, v0
	v_pk_mul_f32 v[84:85], v[76:77], v[74:75]
	v_cvt_pk_bf16_f32 v74, v78, v79
	v_lshl_add_u64 v[78:79], s[42:43], 0, v[192:193]
	v_lshlrev_b32_e32 v0, 16, v166
	v_cvt_pk_bf16_f32 v75, v80, v81
	v_cvt_pk_bf16_f32 v76, v82, v83
	v_cvt_pk_bf16_f32 v77, v84, v85
	v_lshl_add_u64 v[78:79], v[78:79], 0, v[182:183]
	global_store_dwordx4 v[78:79], v[74:77], off
	s_nop 1
	v_max_f32_e32 v74, 0xda24260, v0
	v_and_b32_e32 v0, 0xffff0000, v166
	v_max_f32_e32 v75, 0xda24260, v0
	v_lshlrev_b32_e32 v0, 16, v167
	v_pk_mul_f32 v[70:71], v[70:71], v[74:75]
	v_max_f32_e32 v74, 0xda24260, v0
	v_and_b32_e32 v0, 0xffff0000, v167
	v_max_f32_e32 v75, 0xda24260, v0
	v_lshlrev_b32_e32 v0, 16, v168
	v_pk_mul_f32 v[72:73], v[72:73], v[74:75]
	v_max_f32_e32 v74, 0xda24260, v0
	v_and_b32_e32 v0, 0xffff0000, v168
	v_max_f32_e32 v75, 0xda24260, v0
	v_lshlrev_b32_e32 v0, 16, v169
	v_pk_mul_f32 v[74:75], v[66:67], v[74:75]
	v_max_f32_e32 v66, 0xda24260, v0
	v_and_b32_e32 v0, 0xffff0000, v169
	v_max_f32_e32 v67, 0xda24260, v0
	v_pk_mul_f32 v[76:77], v[68:69], v[66:67]
	v_lshlrev_b32_e32 v0, 16, v162
	v_cvt_pk_bf16_f32 v66, v70, v71
	v_cvt_pk_bf16_f32 v67, v72, v73
	v_cvt_pk_bf16_f32 v68, v74, v75
	v_cvt_pk_bf16_f32 v69, v76, v77
	global_store_dwordx4 v[78:79], v[66:69], off offset:256
	s_nop 1
	v_max_f32_e32 v66, 0xda24260, v0
	v_and_b32_e32 v0, 0xffff0000, v162
	v_max_f32_e32 v67, 0xda24260, v0
	v_lshlrev_b32_e32 v0, 16, v163
	v_pk_mul_f32 v[62:63], v[62:63], v[66:67]
	v_max_f32_e32 v66, 0xda24260, v0
	v_and_b32_e32 v0, 0xffff0000, v163
	v_max_f32_e32 v67, 0xda24260, v0
	v_lshlrev_b32_e32 v0, 16, v164
	v_pk_mul_f32 v[64:65], v[64:65], v[66:67]
	v_max_f32_e32 v66, 0xda24260, v0
	v_and_b32_e32 v0, 0xffff0000, v164
	v_max_f32_e32 v67, 0xda24260, v0
	v_lshlrev_b32_e32 v0, 16, v165
	v_pk_mul_f32 v[58:59], v[58:59], v[66:67]
	v_max_f32_e32 v66, 0xda24260, v0
	v_and_b32_e32 v0, 0xffff0000, v165
	v_max_f32_e32 v67, 0xda24260, v0
	v_pk_mul_f32 v[66:67], v[60:61], v[66:67]
	v_cvt_pk_bf16_f32 v60, v62, v63
	v_cvt_pk_bf16_f32 v62, v58, v59
	v_mov_b64_e32 v[58:59], s[18:19]
	v_mad_i64_i32 v[58:59], s[42:43], v244, s44, v[58:59]
	v_cvt_pk_bf16_f32 v61, v64, v65
	v_lshl_add_u64 v[64:65], v[58:59], 0, v[190:191]
	v_lshlrev_b32_e32 v0, 16, v158
	v_cvt_pk_bf16_f32 v63, v66, v67
	v_lshl_add_u64 v[64:65], v[64:65], 0, v[182:183]
	global_store_dwordx4 v[64:65], v[60:63], off
	s_nop 1
	v_max_f32_e32 v60, 0xda24260, v0
	v_and_b32_e32 v0, 0xffff0000, v158
	v_max_f32_e32 v61, 0xda24260, v0
	v_lshlrev_b32_e32 v0, 16, v159
	v_pk_mul_f32 v[54:55], v[54:55], v[60:61]
	v_max_f32_e32 v60, 0xda24260, v0
	v_and_b32_e32 v0, 0xffff0000, v159
	v_max_f32_e32 v61, 0xda24260, v0
	v_lshlrev_b32_e32 v0, 16, v160
	v_pk_mul_f32 v[56:57], v[56:57], v[60:61]
	v_max_f32_e32 v60, 0xda24260, v0
	v_and_b32_e32 v0, 0xffff0000, v160
	v_max_f32_e32 v61, 0xda24260, v0
	v_lshlrev_b32_e32 v0, 16, v161
	v_pk_mul_f32 v[60:61], v[50:51], v[60:61]
	v_max_f32_e32 v50, 0xda24260, v0
	v_and_b32_e32 v0, 0xffff0000, v161
	v_max_f32_e32 v51, 0xda24260, v0
	v_pk_mul_f32 v[62:63], v[52:53], v[50:51]
	v_lshlrev_b32_e32 v0, 16, v154
	v_cvt_pk_bf16_f32 v50, v54, v55
	v_cvt_pk_bf16_f32 v51, v56, v57
	v_cvt_pk_bf16_f32 v52, v60, v61
	v_cvt_pk_bf16_f32 v53, v62, v63
	global_store_dwordx4 v[64:65], v[50:53], off offset:256
	s_nop 1
	v_max_f32_e32 v50, 0xda24260, v0
	v_and_b32_e32 v0, 0xffff0000, v154
	v_max_f32_e32 v51, 0xda24260, v0
	v_lshlrev_b32_e32 v0, 16, v155
	v_pk_mul_f32 v[46:47], v[46:47], v[50:51]
	v_max_f32_e32 v50, 0xda24260, v0
	v_and_b32_e32 v0, 0xffff0000, v155
	v_max_f32_e32 v51, 0xda24260, v0
	v_lshlrev_b32_e32 v0, 16, v156
	v_pk_mul_f32 v[48:49], v[48:49], v[50:51]
	v_max_f32_e32 v50, 0xda24260, v0
	v_and_b32_e32 v0, 0xffff0000, v156
	v_max_f32_e32 v51, 0xda24260, v0
	v_lshlrev_b32_e32 v0, 16, v157
	v_pk_mul_f32 v[50:51], v[42:43], v[50:51]
	v_max_f32_e32 v42, 0xda24260, v0
	v_and_b32_e32 v0, 0xffff0000, v157
	v_max_f32_e32 v43, 0xda24260, v0
	v_pk_mul_f32 v[52:53], v[44:45], v[42:43]
	v_cvt_pk_bf16_f32 v42, v46, v47
	v_lshl_add_u64 v[46:47], v[58:59], 0, v[188:189]
	v_lshlrev_b32_e32 v0, 16, v150
	v_cvt_pk_bf16_f32 v43, v48, v49
	v_cvt_pk_bf16_f32 v44, v50, v51
	v_cvt_pk_bf16_f32 v45, v52, v53
	v_lshl_add_u64 v[46:47], v[46:47], 0, v[182:183]
	global_store_dwordx4 v[46:47], v[42:45], off
	s_nop 1
	v_max_f32_e32 v42, 0xda24260, v0
	v_and_b32_e32 v0, 0xffff0000, v150
	v_max_f32_e32 v43, 0xda24260, v0
	v_lshlrev_b32_e32 v0, 16, v151
	v_pk_mul_f32 v[38:39], v[38:39], v[42:43]
	v_max_f32_e32 v42, 0xda24260, v0
	v_and_b32_e32 v0, 0xffff0000, v151
	v_max_f32_e32 v43, 0xda24260, v0
	v_lshlrev_b32_e32 v0, 16, v152
	v_pk_mul_f32 v[40:41], v[40:41], v[42:43]
	v_max_f32_e32 v42, 0xda24260, v0
	v_and_b32_e32 v0, 0xffff0000, v152
	v_max_f32_e32 v43, 0xda24260, v0
	v_lshlrev_b32_e32 v0, 16, v153
	v_pk_mul_f32 v[42:43], v[34:35], v[42:43]
	v_max_f32_e32 v34, 0xda24260, v0
	v_and_b32_e32 v0, 0xffff0000, v153
	v_max_f32_e32 v35, 0xda24260, v0
	v_pk_mul_f32 v[44:45], v[36:37], v[34:35]
	v_lshlrev_b32_e32 v0, 16, v146
	v_cvt_pk_bf16_f32 v34, v38, v39
	v_cvt_pk_bf16_f32 v35, v40, v41
	v_cvt_pk_bf16_f32 v36, v42, v43
	v_cvt_pk_bf16_f32 v37, v44, v45
	global_store_dwordx4 v[46:47], v[34:37], off offset:256
	s_nop 1
	v_max_f32_e32 v34, 0xda24260, v0
	v_and_b32_e32 v0, 0xffff0000, v146
	v_max_f32_e32 v35, 0xda24260, v0
	v_lshlrev_b32_e32 v0, 16, v147
	v_pk_mul_f32 v[30:31], v[30:31], v[34:35]
	v_max_f32_e32 v34, 0xda24260, v0
	v_and_b32_e32 v0, 0xffff0000, v147
	v_max_f32_e32 v35, 0xda24260, v0
	v_lshlrev_b32_e32 v0, 16, v148
	v_pk_mul_f32 v[32:33], v[32:33], v[34:35]
	v_max_f32_e32 v34, 0xda24260, v0
	v_and_b32_e32 v0, 0xffff0000, v148
	v_max_f32_e32 v35, 0xda24260, v0
	v_lshlrev_b32_e32 v0, 16, v149
	v_pk_mul_f32 v[34:35], v[26:27], v[34:35]
	v_max_f32_e32 v26, 0xda24260, v0
	v_and_b32_e32 v0, 0xffff0000, v149
	v_max_f32_e32 v27, 0xda24260, v0
	v_pk_mul_f32 v[36:37], v[28:29], v[26:27]
	v_cvt_pk_bf16_f32 v26, v30, v31
	v_lshl_add_u64 v[30:31], v[58:59], 0, v[186:187]
	v_lshlrev_b32_e32 v0, 16, v142
	v_cvt_pk_bf16_f32 v27, v32, v33
	v_cvt_pk_bf16_f32 v28, v34, v35
	v_cvt_pk_bf16_f32 v29, v36, v37
	v_lshl_add_u64 v[30:31], v[30:31], 0, v[182:183]
	global_store_dwordx4 v[30:31], v[26:29], off
	s_nop 1
	v_max_f32_e32 v26, 0xda24260, v0
	v_and_b32_e32 v0, 0xffff0000, v142
	v_max_f32_e32 v27, 0xda24260, v0
	v_lshlrev_b32_e32 v0, 16, v143
	v_pk_mul_f32 v[22:23], v[22:23], v[26:27]
	v_max_f32_e32 v26, 0xda24260, v0
	v_and_b32_e32 v0, 0xffff0000, v143
	v_max_f32_e32 v27, 0xda24260, v0
	v_lshlrev_b32_e32 v0, 16, v144
	v_pk_mul_f32 v[24:25], v[24:25], v[26:27]
	v_max_f32_e32 v26, 0xda24260, v0
	v_and_b32_e32 v0, 0xffff0000, v144
	v_max_f32_e32 v27, 0xda24260, v0
	v_lshlrev_b32_e32 v0, 16, v145
	v_pk_mul_f32 v[26:27], v[18:19], v[26:27]
	v_max_f32_e32 v18, 0xda24260, v0
	v_and_b32_e32 v0, 0xffff0000, v145
	v_max_f32_e32 v19, 0xda24260, v0
	v_pk_mul_f32 v[28:29], v[20:21], v[18:19]
	v_lshlrev_b32_e32 v0, 16, v138
	v_cvt_pk_bf16_f32 v18, v22, v23
	v_cvt_pk_bf16_f32 v19, v24, v25
	v_cvt_pk_bf16_f32 v20, v26, v27
	v_cvt_pk_bf16_f32 v21, v28, v29
	global_store_dwordx4 v[30:31], v[18:21], off offset:256
	s_nop 1
	v_max_f32_e32 v18, 0xda24260, v0
	v_and_b32_e32 v0, 0xffff0000, v138
	v_max_f32_e32 v19, 0xda24260, v0
	v_lshlrev_b32_e32 v0, 16, v139
	v_pk_mul_f32 v[14:15], v[14:15], v[18:19]
	v_max_f32_e32 v18, 0xda24260, v0
	v_and_b32_e32 v0, 0xffff0000, v139
	v_max_f32_e32 v19, 0xda24260, v0
	v_lshlrev_b32_e32 v0, 16, v140
	v_pk_mul_f32 v[16:17], v[16:17], v[18:19]
	v_max_f32_e32 v18, 0xda24260, v0
	v_and_b32_e32 v0, 0xffff0000, v140
	v_max_f32_e32 v19, 0xda24260, v0
	v_lshlrev_b32_e32 v0, 16, v141
	v_pk_mul_f32 v[18:19], v[10:11], v[18:19]
	v_max_f32_e32 v10, 0xda24260, v0
	v_and_b32_e32 v0, 0xffff0000, v141
	v_max_f32_e32 v11, 0xda24260, v0
	v_pk_mul_f32 v[20:21], v[12:13], v[10:11]
	v_cvt_pk_bf16_f32 v10, v14, v15
	v_lshl_add_u64 v[14:15], v[58:59], 0, v[184:185]
	v_lshlrev_b32_e32 v0, 16, v134
	v_cvt_pk_bf16_f32 v11, v16, v17
	v_cvt_pk_bf16_f32 v12, v18, v19
	v_cvt_pk_bf16_f32 v13, v20, v21
	v_lshl_add_u64 v[14:15], v[14:15], 0, v[182:183]
	global_store_dwordx4 v[14:15], v[10:13], off
	s_nop 1
	v_max_f32_e32 v10, 0xda24260, v0
	v_and_b32_e32 v0, 0xffff0000, v134
	v_max_f32_e32 v11, 0xda24260, v0
	v_lshlrev_b32_e32 v0, 16, v135
	v_pk_mul_f32 v[6:7], v[6:7], v[10:11]
	v_max_f32_e32 v10, 0xda24260, v0
	v_and_b32_e32 v0, 0xffff0000, v135
	v_max_f32_e32 v11, 0xda24260, v0
	v_lshlrev_b32_e32 v0, 16, v136
	v_pk_mul_f32 v[8:9], v[8:9], v[10:11]
	v_max_f32_e32 v10, 0xda24260, v0
	v_and_b32_e32 v0, 0xffff0000, v136
	v_max_f32_e32 v11, 0xda24260, v0
	v_lshlrev_b32_e32 v0, 16, v137
	v_pk_mul_f32 v[10:11], v[2:3], v[10:11]
	v_max_f32_e32 v2, 0xda24260, v0
	v_and_b32_e32 v0, 0xffff0000, v137
	v_max_f32_e32 v3, 0xda24260, v0
	v_pk_mul_f32 v[12:13], v[4:5], v[2:3]
	v_cvt_pk_bf16_f32 v2, v6, v7
	v_cvt_pk_bf16_f32 v3, v8, v9
	v_cvt_pk_bf16_f32 v4, v10, v11
	v_cvt_pk_bf16_f32 v5, v12, v13
	global_store_dwordx4 v[14:15], v[2:5], off offset:256
	s_cbranch_vccnz .LBB0_36
	s_andn2_b64 vcc, exec, s[0:1]
	s_cbranch_vccnz .LBB0_35
	s_barrier
	s_branch .LBB0_35

.LBB0_568:
	s_waitcnt vmcnt(0)
	v_mov_b32_e32 v186, v233
	v_mov_b32_e32 v187, v234
	v_mov_b32_e32 v188, v235
	v_mov_b32_e32 v189, v236
	v_mov_b32_e32 v190, v237
	v_mov_b32_e32 v191, v238
	v_mov_b32_e32 v192, v239
	v_mov_b32_e32 v193, v240
	v_permlane16_swap_b32_e32 v233, v186
	v_permlane16_swap_b32_e32 v234, v187
	v_permlane16_swap_b32_e32 v235, v188
	v_permlane16_swap_b32_e32 v236, v189
	v_permlane16_swap_b32_e32 v237, v190
	v_permlane16_swap_b32_e32 v238, v191
	v_permlane16_swap_b32_e32 v239, v192
	v_permlane16_swap_b32_e32 v240, v193
	v_add_f32_e32 v208, v233, v186
	v_add_f32_e32 v209, v234, v187
	v_add_f32_e32 v210, v235, v188
	v_add_f32_e32 v211, v236, v189
	v_add_f32_e32 v212, v237, v190
	v_add_f32_e32 v213, v238, v191
	v_add_f32_e32 v214, v239, v192
	v_add_f32_e32 v215, v240, v193
	v_mov_b32_e32 v186, v208
	v_mov_b32_e32 v187, v209
	v_mov_b32_e32 v188, v210
	v_mov_b32_e32 v189, v211
	v_mov_b32_e32 v190, v212
	v_mov_b32_e32 v191, v213
	v_mov_b32_e32 v192, v214
	v_mov_b32_e32 v193, v215
	v_permlane32_swap_b32_e32 v208, v186
	v_permlane32_swap_b32_e32 v209, v187
	v_permlane32_swap_b32_e32 v210, v188
	v_permlane32_swap_b32_e32 v211, v189
	v_permlane32_swap_b32_e32 v212, v190
	v_permlane32_swap_b32_e32 v213, v191
	v_permlane32_swap_b32_e32 v214, v192
	v_permlane32_swap_b32_e32 v215, v193
	v_add_f32_e32 v208, v208, v186
	v_add_f32_e32 v209, v209, v187
	v_add_f32_e32 v210, v210, v188
	v_add_f32_e32 v211, v211, v189
	v_add_f32_e32 v212, v212, v190
	v_add_f32_e32 v213, v213, v191
	v_add_f32_e32 v214, v214, v192
	v_add_f32_e32 v215, v215, v193
	v_fmamk_f32 v208, v208, 0x3a800000, v222
	v_fmamk_f32 v209, v209, 0x3a800000, v222
	v_fmamk_f32 v210, v210, 0x3a800000, v222
	v_fmamk_f32 v211, v211, 0x3a800000, v222
	v_fmamk_f32 v212, v212, 0x3a800000, v222
	v_fmamk_f32 v213, v213, 0x3a800000, v222
	v_fmamk_f32 v214, v214, 0x3a800000, v222
	v_fmamk_f32 v215, v215, 0x3a800000, v222
	v_mov_b32_e32 v162, v208
	v_mov_b32_e32 v163, v209
	v_mov_b32_e32 v164, v210
	v_mov_b32_e32 v165, v211
	v_mov_b32_e32 v166, v212
	v_mov_b32_e32 v167, v213
	v_mov_b32_e32 v168, v214
	v_mov_b32_e32 v169, v215
	v_rsq_f32_e32 v208, v208
	v_rsq_f32_e32 v209, v209
	v_rsq_f32_e32 v210, v210
	v_rsq_f32_e32 v211, v211
	v_rsq_f32_e32 v212, v212
	v_rsq_f32_e32 v213, v213
	v_rsq_f32_e32 v214, v214
	v_rsq_f32_e32 v215, v215
	s_ashr_i32 s21, s19, 11
	s_mul_hi_i32 s39, s21, 0x1414000
	s_mul_i32 s21, s21, 0x1414000
	v_bitop3_b32 v149, s19, v230, v97 bitop3:0xc8
	s_add_u32 s38, s4, s21
	s_addc_u32 s39, s5, s39
	v_mul_u32_u24_e32 v0, 0xb00, v149
	v_lshlrev_b32_e32 v0, 1, v0
	v_lshl_add_u32 v220, v184, 1, v0
	v_mov_b32_e32 v232, v162
	v_mul_f32_e32 v233, 0xbfb8aa3b, v208
	v_mov_b32_e32 v234, v163
	v_mul_f32_e32 v235, 0xbfb8aa3b, v209
	v_mov_b32_e32 v236, v164
	v_mul_f32_e32 v237, 0xbfb8aa3b, v210
	v_mov_b32_e32 v238, v165
	v_mul_f32_e32 v239, 0xbfb8aa3b, v211
	v_mov_b32_e32 v240, v166
	v_mul_f32_e32 v241, 0xbfb8aa3b, v212
	v_mov_b32_e32 v242, v167
	v_mul_f32_e32 v243, 0xbfb8aa3b, v213
	v_mov_b32_e32 v244, v168
	v_mul_f32_e32 v245, 0xbfb8aa3b, v214
	v_mov_b32_e32 v246, v169
	v_mul_f32_e32 v247, 0xbfb8aa3b, v215
	v_pk_mul_f32 v[208:209], v[130:131], v[232:233] op_sel:[0,1] op_sel_hi:[1,1]
	v_pk_mul_f32 v[210:211], v[132:133], v[232:233] op_sel:[0,1] op_sel_hi:[1,1]
	v_pk_mul_f32 v[212:213], v[126:127], v[232:233] op_sel:[0,1] op_sel_hi:[1,1]
	v_pk_mul_f32 v[214:215], v[128:129], v[232:233] op_sel:[0,1] op_sel_hi:[1,1]
	v_exp_f32_e32 v208, v208
	v_exp_f32_e32 v209, v209
	v_exp_f32_e32 v210, v210
	v_exp_f32_e32 v211, v211
	v_exp_f32_e32 v212, v212
	v_exp_f32_e32 v213, v213
	v_exp_f32_e32 v214, v214
	v_exp_f32_e32 v215, v215
	v_pk_fma_f32 v[208:209], v[208:209], v[232:233], v[232:233] op_sel_hi:[1,0,0]
	v_pk_fma_f32 v[210:211], v[210:211], v[232:233], v[232:233] op_sel_hi:[1,0,0]
	v_pk_fma_f32 v[212:213], v[212:213], v[232:233], v[232:233] op_sel_hi:[1,0,0]
	v_pk_fma_f32 v[214:215], v[214:215], v[232:233], v[232:233] op_sel_hi:[1,0,0]
	v_rcp_f32_e32 v208, v208
	v_rcp_f32_e32 v209, v209
	v_rcp_f32_e32 v210, v210
	v_rcp_f32_e32 v211, v211
	v_rcp_f32_e32 v212, v212
	v_rcp_f32_e32 v213, v213
	v_rcp_f32_e32 v214, v214
	v_rcp_f32_e32 v215, v215
	v_pk_mul_f32 v[130:131], v[130:131], v[122:123]
	v_pk_mul_f32 v[132:133], v[132:133], v[124:125]
	v_pk_mul_f32 v[126:127], v[126:127], v[118:119]
	v_pk_mul_f32 v[128:129], v[128:129], v[120:121]
	v_pk_mul_f32 v[130:131], v[130:131], v[208:209]
	v_pk_mul_f32 v[132:133], v[132:133], v[210:211]
	v_pk_mul_f32 v[126:127], v[126:127], v[212:213]
	v_pk_mul_f32 v[128:129], v[128:129], v[214:215]
	v_cvt_pk_bf16_f32 v216, v130, v131
	v_cvt_pk_bf16_f32 v217, v132, v133
	v_cvt_pk_bf16_f32 v218, v126, v127
	v_cvt_pk_bf16_f32 v219, v128, v129
	global_store_dwordx4 v220, v[216:219], s[38:39]
	v_pk_mul_f32 v[208:209], v[114:115], v[234:235] op_sel:[0,1] op_sel_hi:[1,1]
	v_pk_mul_f32 v[210:211], v[116:117], v[234:235] op_sel:[0,1] op_sel_hi:[1,1]
	v_pk_mul_f32 v[212:213], v[110:111], v[234:235] op_sel:[0,1] op_sel_hi:[1,1]
	v_pk_mul_f32 v[214:215], v[112:113], v[234:235] op_sel:[0,1] op_sel_hi:[1,1]
	v_exp_f32_e32 v208, v208
	v_exp_f32_e32 v209, v209
	v_exp_f32_e32 v210, v210
	v_exp_f32_e32 v211, v211
	v_exp_f32_e32 v212, v212
	v_exp_f32_e32 v213, v213
	v_exp_f32_e32 v214, v214
	v_exp_f32_e32 v215, v215
	v_pk_fma_f32 v[208:209], v[208:209], v[234:235], v[234:235] op_sel_hi:[1,0,0]
	v_pk_fma_f32 v[210:211], v[210:211], v[234:235], v[234:235] op_sel_hi:[1,0,0]
	v_pk_fma_f32 v[212:213], v[212:213], v[234:235], v[234:235] op_sel_hi:[1,0,0]
	v_pk_fma_f32 v[214:215], v[214:215], v[234:235], v[234:235] op_sel_hi:[1,0,0]
	v_rcp_f32_e32 v208, v208
	v_rcp_f32_e32 v209, v209
	v_rcp_f32_e32 v210, v210
	v_rcp_f32_e32 v211, v211
	v_rcp_f32_e32 v212, v212
	v_rcp_f32_e32 v213, v213
	v_rcp_f32_e32 v214, v214
	v_rcp_f32_e32 v215, v215
	v_pk_mul_f32 v[114:115], v[114:115], v[106:107]
	v_pk_mul_f32 v[116:117], v[116:117], v[108:109]
	v_pk_mul_f32 v[110:111], v[110:111], v[102:103]
	v_pk_mul_f32 v[112:113], v[112:113], v[104:105]
	v_pk_mul_f32 v[114:115], v[114:115], v[208:209]
	v_pk_mul_f32 v[116:117], v[116:117], v[210:211]
	v_pk_mul_f32 v[110:111], v[110:111], v[212:213]
	v_pk_mul_f32 v[112:113], v[112:113], v[214:215]
	v_cvt_pk_bf16_f32 v248, v114, v115
	v_cvt_pk_bf16_f32 v249, v116, v117
	v_cvt_pk_bf16_f32 v250, v110, v111
	v_cvt_pk_bf16_f32 v251, v112, v113
	v_add_u32_e32 v221, 0x16000, v220
	global_store_dwordx4 v221, v[248:251], s[38:39]
	v_pk_mul_f32 v[208:209], v[98:99], v[236:237] op_sel:[0,1] op_sel_hi:[1,1]
	v_pk_mul_f32 v[210:211], v[100:101], v[236:237] op_sel:[0,1] op_sel_hi:[1,1]
	v_pk_mul_f32 v[212:213], v[90:91], v[236:237] op_sel:[0,1] op_sel_hi:[1,1]
	v_pk_mul_f32 v[214:215], v[92:93], v[236:237] op_sel:[0,1] op_sel_hi:[1,1]
	v_exp_f32_e32 v208, v208
	v_exp_f32_e32 v209, v209
	v_exp_f32_e32 v210, v210
	v_exp_f32_e32 v211, v211
	v_exp_f32_e32 v212, v212
	v_exp_f32_e32 v213, v213
	v_exp_f32_e32 v214, v214
	v_exp_f32_e32 v215, v215
	v_pk_fma_f32 v[208:209], v[208:209], v[236:237], v[236:237] op_sel_hi:[1,0,0]
	v_pk_fma_f32 v[210:211], v[210:211], v[236:237], v[236:237] op_sel_hi:[1,0,0]
	v_pk_fma_f32 v[212:213], v[212:213], v[236:237], v[236:237] op_sel_hi:[1,0,0]
	v_pk_fma_f32 v[214:215], v[214:215], v[236:237], v[236:237] op_sel_hi:[1,0,0]
	v_rcp_f32_e32 v208, v208
	v_rcp_f32_e32 v209, v209
	v_rcp_f32_e32 v210, v210
	v_rcp_f32_e32 v211, v211
	v_rcp_f32_e32 v212, v212
	v_rcp_f32_e32 v213, v213
	v_rcp_f32_e32 v214, v214
	v_rcp_f32_e32 v215, v215
	v_pk_mul_f32 v[98:99], v[98:99], v[86:87]
	v_pk_mul_f32 v[100:101], v[100:101], v[88:89]
	v_pk_mul_f32 v[90:91], v[90:91], v[82:83]
	v_pk_mul_f32 v[92:93], v[92:93], v[84:85]
	v_pk_mul_f32 v[98:99], v[98:99], v[208:209]
	v_pk_mul_f32 v[100:101], v[100:101], v[210:211]
	v_pk_mul_f32 v[90:91], v[90:91], v[212:213]
	v_pk_mul_f32 v[92:93], v[92:93], v[214:215]
	v_cvt_pk_bf16_f32 v216, v98, v99
	v_cvt_pk_bf16_f32 v217, v100, v101
	v_cvt_pk_bf16_f32 v218, v90, v91
	v_cvt_pk_bf16_f32 v219, v92, v93
	v_add_u32_e32 v221, 0x2c000, v220
	global_store_dwordx4 v221, v[216:219], s[38:39]
	v_pk_mul_f32 v[208:209], v[78:79], v[238:239] op_sel:[0,1] op_sel_hi:[1,1]
	v_pk_mul_f32 v[210:211], v[80:81], v[238:239] op_sel:[0,1] op_sel_hi:[1,1]
	v_pk_mul_f32 v[212:213], v[74:75], v[238:239] op_sel:[0,1] op_sel_hi:[1,1]
	v_pk_mul_f32 v[214:215], v[76:77], v[238:239] op_sel:[0,1] op_sel_hi:[1,1]
	v_exp_f32_e32 v208, v208
	v_exp_f32_e32 v209, v209
	v_exp_f32_e32 v210, v210
	v_exp_f32_e32 v211, v211
	v_exp_f32_e32 v212, v212
	v_exp_f32_e32 v213, v213
	v_exp_f32_e32 v214, v214
	v_exp_f32_e32 v215, v215
	v_pk_fma_f32 v[208:209], v[208:209], v[238:239], v[238:239] op_sel_hi:[1,0,0]
	v_pk_fma_f32 v[210:211], v[210:211], v[238:239], v[238:239] op_sel_hi:[1,0,0]
	v_pk_fma_f32 v[212:213], v[212:213], v[238:239], v[238:239] op_sel_hi:[1,0,0]
	v_pk_fma_f32 v[214:215], v[214:215], v[238:239], v[238:239] op_sel_hi:[1,0,0]
	v_rcp_f32_e32 v208, v208
	v_rcp_f32_e32 v209, v209
	v_rcp_f32_e32 v210, v210
	v_rcp_f32_e32 v211, v211
	v_rcp_f32_e32 v212, v212
	v_rcp_f32_e32 v213, v213
	v_rcp_f32_e32 v214, v214
	v_rcp_f32_e32 v215, v215
	v_pk_mul_f32 v[78:79], v[78:79], v[70:71]
	v_pk_mul_f32 v[80:81], v[80:81], v[72:73]
	v_pk_mul_f32 v[74:75], v[74:75], v[66:67]
	v_pk_mul_f32 v[76:77], v[76:77], v[68:69]
	v_pk_mul_f32 v[78:79], v[78:79], v[208:209]
	v_pk_mul_f32 v[80:81], v[80:81], v[210:211]
	v_pk_mul_f32 v[74:75], v[74:75], v[212:213]
	v_pk_mul_f32 v[76:77], v[76:77], v[214:215]
	v_cvt_pk_bf16_f32 v248, v78, v79
	v_cvt_pk_bf16_f32 v249, v80, v81
	v_cvt_pk_bf16_f32 v250, v74, v75
	v_cvt_pk_bf16_f32 v251, v76, v77
	v_add_u32_e32 v221, 0x42000, v220
	global_store_dwordx4 v221, v[248:251], s[38:39]
	v_pk_mul_f32 v[208:209], v[62:63], v[240:241] op_sel:[0,1] op_sel_hi:[1,1]
	v_pk_mul_f32 v[210:211], v[64:65], v[240:241] op_sel:[0,1] op_sel_hi:[1,1]
	v_pk_mul_f32 v[212:213], v[58:59], v[240:241] op_sel:[0,1] op_sel_hi:[1,1]
	v_pk_mul_f32 v[214:215], v[60:61], v[240:241] op_sel:[0,1] op_sel_hi:[1,1]
	v_exp_f32_e32 v208, v208
	v_exp_f32_e32 v209, v209
	v_exp_f32_e32 v210, v210
	v_exp_f32_e32 v211, v211
	v_exp_f32_e32 v212, v212
	v_exp_f32_e32 v213, v213
	v_exp_f32_e32 v214, v214
	v_exp_f32_e32 v215, v215
	v_pk_fma_f32 v[208:209], v[208:209], v[240:241], v[240:241] op_sel_hi:[1,0,0]
	v_pk_fma_f32 v[210:211], v[210:211], v[240:241], v[240:241] op_sel_hi:[1,0,0]
	v_pk_fma_f32 v[212:213], v[212:213], v[240:241], v[240:241] op_sel_hi:[1,0,0]
	v_pk_fma_f32 v[214:215], v[214:215], v[240:241], v[240:241] op_sel_hi:[1,0,0]
	v_rcp_f32_e32 v208, v208
	v_rcp_f32_e32 v209, v209
	v_rcp_f32_e32 v210, v210
	v_rcp_f32_e32 v211, v211
	v_rcp_f32_e32 v212, v212
	v_rcp_f32_e32 v213, v213
	v_rcp_f32_e32 v214, v214
	v_rcp_f32_e32 v215, v215
	v_pk_mul_f32 v[62:63], v[62:63], v[54:55]
	v_pk_mul_f32 v[64:65], v[64:65], v[56:57]
	v_pk_mul_f32 v[58:59], v[58:59], v[50:51]
	v_pk_mul_f32 v[60:61], v[60:61], v[52:53]
	v_pk_mul_f32 v[62:63], v[62:63], v[208:209]
	v_pk_mul_f32 v[64:65], v[64:65], v[210:211]
	v_pk_mul_f32 v[58:59], v[58:59], v[212:213]
	v_pk_mul_f32 v[60:61], v[60:61], v[214:215]
	v_cvt_pk_bf16_f32 v216, v62, v63
	v_cvt_pk_bf16_f32 v217, v64, v65
	v_cvt_pk_bf16_f32 v218, v58, v59
	v_cvt_pk_bf16_f32 v219, v60, v61
	v_add_u32_e32 v221, 0xb0000, v220
	global_store_dwordx4 v221, v[216:219], s[38:39]
	v_pk_mul_f32 v[208:209], v[46:47], v[242:243] op_sel:[0,1] op_sel_hi:[1,1]
	v_pk_mul_f32 v[210:211], v[48:49], v[242:243] op_sel:[0,1] op_sel_hi:[1,1]
	v_pk_mul_f32 v[212:213], v[42:43], v[242:243] op_sel:[0,1] op_sel_hi:[1,1]
	v_pk_mul_f32 v[214:215], v[44:45], v[242:243] op_sel:[0,1] op_sel_hi:[1,1]
	v_exp_f32_e32 v208, v208
	v_exp_f32_e32 v209, v209
	v_exp_f32_e32 v210, v210
	v_exp_f32_e32 v211, v211
	v_exp_f32_e32 v212, v212
	v_exp_f32_e32 v213, v213
	v_exp_f32_e32 v214, v214
	v_exp_f32_e32 v215, v215
	v_pk_fma_f32 v[208:209], v[208:209], v[242:243], v[242:243] op_sel_hi:[1,0,0]
	v_pk_fma_f32 v[210:211], v[210:211], v[242:243], v[242:243] op_sel_hi:[1,0,0]
	v_pk_fma_f32 v[212:213], v[212:213], v[242:243], v[242:243] op_sel_hi:[1,0,0]
	v_pk_fma_f32 v[214:215], v[214:215], v[242:243], v[242:243] op_sel_hi:[1,0,0]
	v_rcp_f32_e32 v208, v208
	v_rcp_f32_e32 v209, v209
	v_rcp_f32_e32 v210, v210
	v_rcp_f32_e32 v211, v211
	v_rcp_f32_e32 v212, v212
	v_rcp_f32_e32 v213, v213
	v_rcp_f32_e32 v214, v214
	v_rcp_f32_e32 v215, v215
	v_pk_mul_f32 v[46:47], v[46:47], v[38:39]
	v_pk_mul_f32 v[48:49], v[48:49], v[40:41]
	v_pk_mul_f32 v[42:43], v[42:43], v[34:35]
	v_pk_mul_f32 v[44:45], v[44:45], v[36:37]
	v_pk_mul_f32 v[46:47], v[46:47], v[208:209]
	v_pk_mul_f32 v[48:49], v[48:49], v[210:211]
	v_pk_mul_f32 v[42:43], v[42:43], v[212:213]
	v_pk_mul_f32 v[44:45], v[44:45], v[214:215]
	v_cvt_pk_bf16_f32 v248, v46, v47
	v_cvt_pk_bf16_f32 v249, v48, v49
	v_cvt_pk_bf16_f32 v250, v42, v43
	v_cvt_pk_bf16_f32 v251, v44, v45
	v_add_u32_e32 v221, 0xc6000, v220
	global_store_dwordx4 v221, v[248:251], s[38:39]
	v_pk_mul_f32 v[208:209], v[30:31], v[244:245] op_sel:[0,1] op_sel_hi:[1,1]
	v_pk_mul_f32 v[210:211], v[32:33], v[244:245] op_sel:[0,1] op_sel_hi:[1,1]
	v_pk_mul_f32 v[212:213], v[26:27], v[244:245] op_sel:[0,1] op_sel_hi:[1,1]
	v_pk_mul_f32 v[214:215], v[28:29], v[244:245] op_sel:[0,1] op_sel_hi:[1,1]
	v_exp_f32_e32 v208, v208
	v_exp_f32_e32 v209, v209
	v_exp_f32_e32 v210, v210
	v_exp_f32_e32 v211, v211
	v_exp_f32_e32 v212, v212
	v_exp_f32_e32 v213, v213
	v_exp_f32_e32 v214, v214
	v_exp_f32_e32 v215, v215
	v_pk_fma_f32 v[208:209], v[208:209], v[244:245], v[244:245] op_sel_hi:[1,0,0]
	v_pk_fma_f32 v[210:211], v[210:211], v[244:245], v[244:245] op_sel_hi:[1,0,0]
	v_pk_fma_f32 v[212:213], v[212:213], v[244:245], v[244:245] op_sel_hi:[1,0,0]
	v_pk_fma_f32 v[214:215], v[214:215], v[244:245], v[244:245] op_sel_hi:[1,0,0]
	v_rcp_f32_e32 v208, v208
	v_rcp_f32_e32 v209, v209
	v_rcp_f32_e32 v210, v210
	v_rcp_f32_e32 v211, v211
	v_rcp_f32_e32 v212, v212
	v_rcp_f32_e32 v213, v213
	v_rcp_f32_e32 v214, v214
	v_rcp_f32_e32 v215, v215
	v_pk_mul_f32 v[30:31], v[30:31], v[22:23]
	v_pk_mul_f32 v[32:33], v[32:33], v[24:25]
	v_pk_mul_f32 v[26:27], v[26:27], v[18:19]
	v_pk_mul_f32 v[28:29], v[28:29], v[20:21]
	v_pk_mul_f32 v[30:31], v[30:31], v[208:209]
	v_pk_mul_f32 v[32:33], v[32:33], v[210:211]
	v_pk_mul_f32 v[26:27], v[26:27], v[212:213]
	v_pk_mul_f32 v[28:29], v[28:29], v[214:215]
	v_cvt_pk_bf16_f32 v216, v30, v31
	v_cvt_pk_bf16_f32 v217, v32, v33
	v_cvt_pk_bf16_f32 v218, v26, v27
	v_cvt_pk_bf16_f32 v219, v28, v29
	v_add_u32_e32 v221, 0xdc000, v220
	global_store_dwordx4 v221, v[216:219], s[38:39]
	v_pk_mul_f32 v[208:209], v[14:15], v[246:247] op_sel:[0,1] op_sel_hi:[1,1]
	v_pk_mul_f32 v[210:211], v[16:17], v[246:247] op_sel:[0,1] op_sel_hi:[1,1]
	v_pk_mul_f32 v[212:213], v[10:11], v[246:247] op_sel:[0,1] op_sel_hi:[1,1]
	v_pk_mul_f32 v[214:215], v[12:13], v[246:247] op_sel:[0,1] op_sel_hi:[1,1]
	v_exp_f32_e32 v208, v208
	v_exp_f32_e32 v209, v209
	v_exp_f32_e32 v210, v210
	v_exp_f32_e32 v211, v211
	v_exp_f32_e32 v212, v212
	v_exp_f32_e32 v213, v213
	v_exp_f32_e32 v214, v214
	v_exp_f32_e32 v215, v215
	v_pk_fma_f32 v[208:209], v[208:209], v[246:247], v[246:247] op_sel_hi:[1,0,0]
	v_pk_fma_f32 v[210:211], v[210:211], v[246:247], v[246:247] op_sel_hi:[1,0,0]
	v_pk_fma_f32 v[212:213], v[212:213], v[246:247], v[246:247] op_sel_hi:[1,0,0]
	v_pk_fma_f32 v[214:215], v[214:215], v[246:247], v[246:247] op_sel_hi:[1,0,0]
	v_rcp_f32_e32 v208, v208
	v_rcp_f32_e32 v209, v209
	v_rcp_f32_e32 v210, v210
	v_rcp_f32_e32 v211, v211
	v_rcp_f32_e32 v212, v212
	v_rcp_f32_e32 v213, v213
	v_rcp_f32_e32 v214, v214
	v_rcp_f32_e32 v215, v215
	v_pk_mul_f32 v[14:15], v[14:15], v[6:7]
	v_pk_mul_f32 v[16:17], v[16:17], v[8:9]
	v_pk_mul_f32 v[10:11], v[10:11], v[2:3]
	v_pk_mul_f32 v[12:13], v[12:13], v[4:5]
	v_pk_mul_f32 v[14:15], v[14:15], v[208:209]
	v_pk_mul_f32 v[16:17], v[16:17], v[210:211]
	v_pk_mul_f32 v[10:11], v[10:11], v[212:213]
	v_pk_mul_f32 v[12:13], v[12:13], v[214:215]
	v_cvt_pk_bf16_f32 v248, v14, v15
	v_cvt_pk_bf16_f32 v249, v16, v17
	v_cvt_pk_bf16_f32 v250, v10, v11
	v_cvt_pk_bf16_f32 v251, v12, v13
	v_add_u32_e32 v221, 0xf2000, v220
	global_store_dwordx4 v221, v[248:251], s[38:39]
	s_mov_b32 s21, 0x16000
	s_mov_b32 s40, 0x2c000
	s_mov_b32 s19, 0x1414000
	s_andn2_b64 vcc, exec, s[36:37]
	s_mov_b64 s[36:37], -1
	s_cbranch_vccnz .LBB0_561
	s_andn2_b64 vcc, exec, s[0:1]
	s_cbranch_vccnz .LBB0_560
	s_barrier
	s_branch .LBB0_560
